# P2 static deal of the pooling units reworked: 32 workgroups get a single light unit (they then take two memory-attention units from the dynamic queue), the rest are dealt in snake order
# speedup vs baseline: 1.0046x; 1.0003x over previous
.LBB0_508:
	s_and_b64 vcc, exec, s[0:1]
	s_cbranch_vccz .LBB0_510
	v_readlane_b32 s0, v253, 18
	v_readlane_b32 s1, v253, 19
	s_andn2_b64 vcc, exec, s[0:1]
	s_add_i32 s98, s2, 0x120
	s_cmp_eq_u32 s3, 0x100
	s_cselect_b32 s98, s98, s2
	s_cmpk_gt_u32 s2, 0xdf
	s_cselect_b32 s20, s98, s2
	s_cbranch_vccz .LBB0_558

.LBB0_557:
	s_cmp_eq_u32 s3, 0x100
	s_cbranch_scc1 .Lpool_next
	s_add_i32 s20, s20, s3
	s_cmpk_gt_i32 s20, 0x21f
	s_cbranch_scc1 .LBB0_510
	s_branch .LBB0_558
.Lpool_next:
	s_cmpk_gt_u32 s2, 0xdf
	s_cbranch_scc1 .LBB0_510
	s_cmp_eq_u32 s20, s2
	s_cbranch_scc0 .Lpool_r1done
	s_sub_i32 s20, 0x1bf, s2
	s_branch .LBB0_558
.Lpool_r1done:
	s_cmpk_gt_u32 s20, 0x1bf
	s_cbranch_scc1 .LBB0_510
	s_add_i32 s98, s2, 0xffffff78
	s_cmpk_lt_u32 s98, 64
	s_cbranch_scc0 .LBB0_510
	s_add_i32 s20, s2, 0x138
